# v49: v48 + phase-1 gate reduce last two butterfly stages via v_permlane16/32_swap instead of ds_bpermute
# baseline (speedup 1.0000x reference)
; __device__ __forceinline__ float dot4(const f32x4 a, const f32x4 b) { return (a[0] * b[0] + a[1] * b[1]) + (a[2] * b[2] + a[3] * b[3]); }
; __device__ __forceinline__ void norm_rows2(const f32x4 (&xa)[4], const f32x4 (&xb)[4], const LAS float* gsa, const LAS float* sha, const LAS float* gsb, const LAS float* shb, const LAS float* WgT, ...
;     float ssa = 0.f, ssb = 0.f;
; #pragma unroll
;     for (int i = 0; i < 4; ++i) { ssa += dot4(xa[i], xa[i]); ssb += dot4(xb[i], xb[i]); }
;     ssa = wave_sum(ssa); ssb = wave_sum(ssb);
; __device__ void phase1(const Params& p, LAS unsigned char* lds) {
;     ...
;         for (int pr = 0; pr < 5; ++pr) {
;             const int ra_ = pr < 4 ? rbase + 2 * pr : rbase + 7;
;             const float* xa_ = p.x + (size_t)ra_ * 1024; const float* xb_ = pr < 4 ? xa_ + 1024 : p.ctx + (size_t)crow * 1024;
;             f32x4 xa[4], xb[4];
; #pragma unroll
;             for (int i = 0; i < 4; ++i) { xa[i] = __builtin_nontemporal_load((const f32x4*)(xa_ + i * 256 + lane * 4)); xb[i] = __builtin_nontemporal_load((const f32x4*)(xb_ + i * 256 + lane * 4)); }
.LBB0_110:
	s_add_i32 s28, 0, 0x2000
	s_add_i32 s29, 0, 0x3000
	s_add_i32 s30, 0, 0x1000
	s_cmp_eq_u32 s82, 8
	v_add_u32_e32 v0, s82, v105
	s_cselect_b64 vcc, -1, 0
	v_cndmask_b32_e32 v60, v0, v108, vcc
	v_ashrrev_i32_e32 v61, 31, v60
	v_lshlrev_b64 v[0:1], 12, v[60:61]
	v_lshl_add_u64 v[0:1], s[36:37], 0, v[0:1]
	v_mov_b32_e32 v49, v35
	s_waitcnt lgkmcnt(0)
	v_lshl_add_u64 v[2:3], v[0:1], 0, v[48:49]
	s_mov_b64 s[38:39], 0x1000
	global_load_dwordx4 v[24:27], v[2:3], off nt
	global_load_dwordx4 v[20:23], v[2:3], off offset:1024 nt
	global_load_dwordx4 v[4:7], v[2:3], off offset:3072 nt
	global_load_dwordx4 v[12:15], v[2:3], off offset:2048 nt
	v_lshl_add_u64 v[0:1], v[0:1], 0, s[38:39]
	v_cndmask_b32_e32 v1, v1, v59, vcc
	v_cndmask_b32_e32 v0, v0, v58, vcc
	v_lshl_add_u64 v[8:9], v[0:1], 0, v[48:49]
	global_load_dwordx4 v[28:31], v[8:9], off nt
	global_load_dwordx4 v[16:19], v[8:9], off offset:1024 nt
	global_load_dwordx4 v[0:3], v[8:9], off offset:3072 nt
	s_nop 0
	global_load_dwordx4 v[8:11], v[8:9], off offset:2048 nt
	s_and_b64 s[38:39], vcc, exec
	s_cselect_b32 s28, s28, 0
	s_cselect_b32 s29, s29, s30
	s_waitcnt vmcnt(7)
	v_pk_mul_f32 v[62:63], v[26:27], v[26:27]
	v_pk_mul_f32 v[64:65], v[24:25], v[24:25]
	s_waitcnt vmcnt(6)
	v_pk_mul_f32 v[66:67], v[22:23], v[22:23]
	v_pk_mul_f32 v[68:69], v[20:21], v[20:21]
	s_waitcnt vmcnt(4)
	v_mul_f32_e32 v70, v15, v15
	v_pk_mov_b32 v[72:73], v[64:65], v[62:63] op_sel:[1,0]
	v_mov_b32_e32 v65, v63
	v_pk_mov_b32 v[62:63], v[68:69], v[66:67] op_sel:[1,0]
	v_mov_b32_e32 v69, v67
	v_mul_f32_e32 v80, v7, v7
	v_mul_f32_e32 v34, v13, v13
	v_pk_fma_f32 v[70:71], v[14:15], v[14:15], v[70:71] op_sel_hi:[1,1,0]
	v_pk_add_f32 v[64:65], v[72:73], v[64:65]
	s_waitcnt vmcnt(3)
	v_pk_mul_f32 v[72:73], v[30:31], v[30:31]
	v_pk_mul_f32 v[74:75], v[28:29], v[28:29]
	v_pk_add_f32 v[62:63], v[62:63], v[68:69]
	s_waitcnt vmcnt(2)
	v_pk_mul_f32 v[68:69], v[18:19], v[18:19]
	v_pk_mul_f32 v[76:77], v[16:17], v[16:17]
	v_mul_f32_e32 v49, v4, v4
	v_mul_f32_e32 v79, v5, v5
	v_mul_f32_e32 v78, v6, v6
	v_pk_fma_f32 v[66:67], v[12:13], v[12:13], v[34:35] op_sel_hi:[1,1,0]
	v_mov_b32_e32 v71, v80
	v_pk_mov_b32 v[80:81], v[74:75], v[72:73] op_sel:[1,0]
	v_mov_b32_e32 v75, v73
	v_pk_mov_b32 v[72:73], v[76:77], v[68:69] op_sel:[1,0]
	v_mov_b32_e32 v77, v69
	v_pk_add_f32 v[64:65], v[64:65], v[64:65] op_sel:[0,1] op_sel_hi:[1,0]
	v_pk_add_f32 v[62:63], v[62:63], v[62:63] op_sel:[0,1] op_sel_hi:[1,0]
	v_mov_b32_e32 v67, v78
	s_waitcnt vmcnt(0)
	v_mul_f32_e32 v34, v9, v9
	v_mul_f32_e32 v78, v11, v11
	v_pk_add_f32 v[74:75], v[80:81], v[74:75]
	v_pk_add_f32 v[72:73], v[72:73], v[76:77]
	v_mov_b32_e32 v65, v49
	v_mov_b32_e32 v63, v79
	v_mul_f32_e32 v82, v0, v0
	v_mul_f32_e32 v83, v1, v1
	v_mul_f32_e32 v84, v2, v2
	v_mul_f32_e32 v85, v3, v3
	v_pk_add_f32 v[66:67], v[66:67], v[70:71]
	v_pk_fma_f32 v[68:69], v[8:9], v[8:9], v[34:35] op_sel_hi:[1,1,0]
	v_pk_fma_f32 v[70:71], v[10:11], v[10:11], v[78:79] op_sel_hi:[1,1,0]
	v_pk_add_f32 v[62:63], v[64:65], v[62:63]
	v_pk_add_f32 v[64:65], v[74:75], v[74:75] op_sel:[0,1] op_sel_hi:[1,0]
	v_pk_add_f32 v[72:73], v[72:73], v[72:73] op_sel:[0,1] op_sel_hi:[1,0]
	v_mov_b32_e32 v69, v84
	v_mov_b32_e32 v71, v85
	v_mov_b32_e32 v65, v82
	v_mov_b32_e32 v73, v83
	v_pk_add_f32 v[68:69], v[68:69], v[70:71]
	v_pk_add_f32 v[64:65], v[64:65], v[72:73]
	v_pk_add_f32 v[62:63], v[62:63], v[66:67]
	v_pk_add_f32 v[64:65], v[64:65], v[68:69]
	v_mov_b32_e32 v67, v62
	v_mov_b32_e32 v66, v64
	v_mov_b32_e32 v62, v65
	v_pk_add_f32 v[62:63], v[66:67], v[62:63]
	v_lshlrev_b64 v[76:77], 11, v[60:61]
	v_add_u32_e32 v49, s28, v48
	v_add_u32_e32 v61, s29, v48
	v_add_u32_e32 v34, 1, v60
	ds_read_b128 v[64:67], v99
	ds_read_b128 v[68:71], v99 offset:4096
	ds_read_b128 v[80:83], v49
	ds_read_b128 v[84:87], v61
	v_add_f32_dpp v62, v62, v62 row_mirror row_mask:0xf bank_mask:0xf
	v_add_f32_dpp v63, v63, v63 row_mirror row_mask:0xf bank_mask:0xf
	v_cndmask_b32_e32 v74, v34, v109, vcc
	v_add_f32_dpp v62, v62, v62 row_half_mirror row_mask:0xf bank_mask:0xf
	v_add_f32_dpp v63, v63, v63 row_half_mirror row_mask:0xf bank_mask:0xf
	v_ashrrev_i32_e32 v75, 31, v74
	v_add_f32_dpp v62, v62, v62 quad_perm:[1,0,3,2] row_mask:0xf bank_mask:0xf
	v_add_f32_dpp v63, v63, v63 quad_perm:[1,0,3,2] row_mask:0xf bank_mask:0xf
	v_lshlrev_b64 v[74:75], 11, v[74:75]
	v_add_f32_dpp v62, v62, v62 quad_perm:[2,3,0,1] row_mask:0xf bank_mask:0xf
	v_add_f32_dpp v63, v63, v63 quad_perm:[2,3,0,1] row_mask:0xf bank_mask:0xf
	v_lshl_add_u64 v[78:79], v[36:37], 0, v[76:77]
	s_nop 0
	v_readlane_b32 s54, v62, 0
	v_readlane_b32 s55, v62, 16
	v_readlane_b32 s56, v62, 32
	v_readlane_b32 s57, v62, 48
	v_readlane_b32 s58, v63, 0
	v_readlane_b32 s59, v63, 16
	v_readlane_b32 s60, v63, 32
	v_readlane_b32 s61, v63, 48
	v_mov_b32_e32 v62, s54
	v_mov_b32_e32 v63, s58
	v_add_f32_e32 v62, s55, v62
	v_add_f32_e32 v63, s59, v63
	v_add_f32_e32 v62, s56, v62
	v_add_f32_e32 v63, s60, v63
	v_add_f32_e32 v62, s57, v62
	v_add_f32_e32 v63, s61, v63
	s_waitcnt lgkmcnt(0)
; #define LAS __attribute__((address_space(3)))
; __device__ __forceinline__ unsigned cvt_pk_bf16(float lo, float hi) { unsigned r; asm volatile("v_cvt_pk_bf16_f32 %0, %1, %2" : "=v"(r) : "v"(lo), "v"(hi)); return r; }
; __device__ __forceinline__ float dot4(const f32x4 a, const f32x4 b) { return (a[0] * b[0] + a[1] * b[1]) + (a[2] * b[2] + a[3] * b[3]); }
; __device__ __forceinline__ void norm_rows2(const f32x4 (&xa)[4], const f32x4 (&xb)[4], const LAS float* gsa, const LAS float* sha, const LAS float* gsb, const LAS float* shb, const LAS float* WgT, ...
;     ...
;     const float ra = rsqrtf(ssa * (1.0f / 1024.0f) + 1e-6f), rb = rsqrtf(ssb * (1.0f / 1024.0f) + 1e-6f);
;     f32x4 ya[4], yb[4];
; #pragma unroll
;     for (int i = 0; i < 4; ++i) {
;         ya[i] = xa[i] * ra * *(const LAS f32x4*)(gsa + i * 256 + lane * 4) + *(const LAS f32x4*)(sha + i * 256 + lane * 4);
;         yb[i] = xb[i] * rb * *(const LAS f32x4*)(gsb + i * 256 + lane * 4) + *(const LAS f32x4*)(shb + i * 256 + lane * 4);
;         u32x2 w; w.x = cvt_pk_bf16(ya[i][0], ya[i][1]); w.y = cvt_pk_bf16(ya[i][2], ya[i][3]); *(u32x2*)(oa + i * 256 + lane * 4) = w;
;         u32x2 v; v.x = cvt_pk_bf16(yb[i][0], yb[i][1]); v.y = cvt_pk_bf16(yb[i][2], yb[i][3]); *(u32x2*)(ob + i * 256 + lane * 4) = v; }
;     f32x4 pa[4], pb[4];
; #pragma unroll
;     for (int jq = 0; jq < 4; ++jq) { f32x4 sa = (f32x4){0.f, 0.f, 0.f, 0.f}, sb = sa;
; #pragma unroll
;         for (int i = 0; i < 4; ++i) { const LAS float* wp = WgT + (jq * 4) * 1024 + i * 256 + lane * 4;
;             const f32x4 w0 = *(const LAS f32x4*)wp, w1 = *(const LAS f32x4*)(wp + 1024), w2 = *(const LAS f32x4*)(wp + 2048), w3 = *(const LAS f32x4*)(wp + 3072);
;             sa += (f32x4){dot4(ya[i], w0), dot4(ya[i], w1), dot4(ya[i], w2), dot4(ya[i], w3)};
;             sb += (f32x4){dot4(yb[i], w0), dot4(yb[i], w1), dot4(yb[i], w2), dot4(yb[i], w3)}; }
	s_nop 0
	v_pk_fma_f32 v[62:63], v[62:63], s[46:47], v[50:51] op_sel_hi:[1,0,0]
	s_nop 0
	v_mul_f32_e32 v72, 0x4b800000, v63
	v_cmp_gt_f32_e64 s[28:29], s34, v63
	v_mul_f32_e32 v73, 0x4b800000, v62
	v_cmp_gt_f32_e64 s[30:31], s34, v62
	v_cndmask_b32_e64 v63, v63, v72, s[28:29]
	v_rsq_f32_e32 v72, v63
	v_cndmask_b32_e64 v62, v62, v73, s[30:31]
	v_rsq_f32_e32 v73, v62
	v_lshl_add_u64 v[62:63], v[36:37], 0, v[74:75]
	v_mul_f32_e32 v74, 0x45800000, v72
	v_cndmask_b32_e64 v88, v72, v74, s[28:29]
	v_mul_f32_e32 v75, 0x45800000, v73
	v_cndmask_b32_e64 v90, v73, v75, s[30:31]
	v_pk_mul_f32 v[24:25], v[24:25], v[88:89] op_sel_hi:[1,0]
	v_pk_mul_f32 v[26:27], v[26:27], v[88:89] op_sel_hi:[1,0]
	v_pk_mul_f32 v[28:29], v[28:29], v[90:91] op_sel_hi:[1,0]
	v_pk_mul_f32 v[30:31], v[30:31], v[90:91] op_sel_hi:[1,0]
	v_pk_mul_f32 v[92:93], v[20:21], v[88:89] op_sel_hi:[1,0]
	v_pk_fma_f32 v[74:75], v[66:67], v[26:27], v[70:71]
	v_pk_fma_f32 v[76:77], v[64:65], v[24:25], v[68:69]
	v_pk_mul_f32 v[110:111], v[22:23], v[88:89] op_sel_hi:[1,0]
	v_cvt_pk_bf16_f32 v20, v76, v77
	v_cvt_pk_bf16_f32 v21, v74, v75
	v_pk_fma_f32 v[70:71], v[82:83], v[30:31], v[86:87]
	v_pk_fma_f32 v[72:73], v[80:81], v[28:29], v[84:85]
	global_store_dwordx2 v[78:79], v[20:21], off
	v_cvt_pk_bf16_f32 v64, v72, v73
	v_cvt_pk_bf16_f32 v65, v70, v71
	ds_read_b128 v[20:23], v99 offset:1024
	ds_read_b128 v[24:27], v99 offset:5120
	ds_read_b128 v[28:31], v49 offset:1024
	ds_read_b128 v[80:83], v61 offset:1024
	v_pk_mul_f32 v[16:17], v[16:17], v[90:91] op_sel_hi:[1,0]
	global_store_dwordx2 v[62:63], v[64:65], off
	v_pk_mul_f32 v[18:19], v[18:19], v[90:91] op_sel_hi:[1,0]
	s_waitcnt lgkmcnt(2)
	v_pk_fma_f32 v[66:67], v[110:111], v[22:23], v[26:27]
	v_pk_fma_f32 v[68:69], v[92:93], v[20:21], v[24:25]
	s_waitcnt lgkmcnt(0)
	v_pk_fma_f32 v[64:65], v[16:17], v[28:29], v[80:81]
	v_cvt_pk_bf16_f32 v16, v68, v69
	v_cvt_pk_bf16_f32 v17, v66, v67
	v_pk_fma_f32 v[30:31], v[18:19], v[30:31], v[82:83]
	global_store_dwordx2 v[78:79], v[16:17], off offset:512
	v_cvt_pk_bf16_f32 v16, v64, v65
	v_cvt_pk_bf16_f32 v17, v30, v31
	global_store_dwordx2 v[62:63], v[16:17], off offset:512
	ds_read_b128 v[16:19], v99 offset:2048
	ds_read_b128 v[20:23], v99 offset:6144
	ds_read_b128 v[24:27], v49 offset:2048
	ds_read_b128 v[80:83], v61 offset:2048
	v_pk_mul_f32 v[12:13], v[12:13], v[88:89] op_sel_hi:[1,0]
	v_pk_mul_f32 v[14:15], v[14:15], v[88:89] op_sel_hi:[1,0]
	v_pk_mul_f32 v[8:9], v[8:9], v[90:91] op_sel_hi:[1,0]
	s_waitcnt lgkmcnt(2)
	v_pk_fma_f32 v[14:15], v[14:15], v[18:19], v[22:23]
	v_pk_fma_f32 v[18:19], v[12:13], v[16:17], v[20:21]
	v_pk_mul_f32 v[10:11], v[10:11], v[90:91] op_sel_hi:[1,0]
	s_waitcnt lgkmcnt(0)
	v_pk_fma_f32 v[20:21], v[8:9], v[24:25], v[80:81]
	v_cvt_pk_bf16_f32 v8, v18, v19
	v_cvt_pk_bf16_f32 v9, v14, v15
	v_pk_fma_f32 v[16:17], v[10:11], v[26:27], v[82:83]
	global_store_dwordx2 v[78:79], v[8:9], off offset:1024
	v_cvt_pk_bf16_f32 v8, v20, v21
	v_cvt_pk_bf16_f32 v9, v16, v17
	global_store_dwordx2 v[62:63], v[8:9], off offset:1024
	ds_read_b128 v[8:11], v99 offset:3072
	ds_read_b128 v[22:25], v99 offset:7168
	v_pk_mul_f32 v[12:13], v[4:5], v[88:89] op_sel_hi:[1,0]
	v_pk_mul_f32 v[80:81], v[6:7], v[88:89] op_sel_hi:[1,0]
	ds_read_b128 v[4:7], v49 offset:3072
	ds_read_b128 v[26:29], v61 offset:3072
	v_pk_mul_f32 v[0:1], v[0:1], v[90:91] op_sel_hi:[1,0]
	s_waitcnt lgkmcnt(2)
	v_pk_fma_f32 v[10:11], v[80:81], v[10:11], v[24:25]
	v_pk_fma_f32 v[12:13], v[12:13], v[8:9], v[22:23]
	v_pk_mul_f32 v[2:3], v[2:3], v[90:91] op_sel_hi:[1,0]
	s_waitcnt lgkmcnt(0)
	v_pk_fma_f32 v[8:9], v[0:1], v[4:5], v[26:27]
	v_cvt_pk_bf16_f32 v0, v12, v13
	v_cvt_pk_bf16_f32 v1, v10, v11
	v_pk_fma_f32 v[6:7], v[2:3], v[6:7], v[28:29]
	global_store_dwordx2 v[78:79], v[0:1], off offset:1536
	v_cvt_pk_bf16_f32 v4, v8, v9
	v_cvt_pk_bf16_f32 v5, v6, v7
	global_store_dwordx2 v[62:63], v[4:5], off offset:1536
	ds_read_b128 v[110:113], v99 offset:16384
	ds_read_b128 v[114:117], v99 offset:20480
	ds_read_b128 v[118:121], v99 offset:24576
	ds_read_b128 v[122:125], v99 offset:28672
	ds_read_b128 v[126:129], v99 offset:32768
	ds_read_b128 v[130:133], v99 offset:36864
	ds_read_b128 v[134:137], v99 offset:40960
	ds_read_b128 v[138:141], v99 offset:45056
	ds_read_b128 v[142:145], v99 offset:49152
	ds_read_b128 v[146:149], v99 offset:53248
	ds_read_b128 v[150:153], v99 offset:57344
	ds_read_b128 v[154:157], v99 offset:61440
	s_waitcnt lgkmcnt(8)
	v_pk_mul_f32 v[160:161], v[72:73], v[110:111]
	v_pk_mul_f32 v[192:193], v[76:77], v[110:111]
	v_pk_mul_f32 v[162:163], v[72:73], v[114:115]
	v_pk_mul_f32 v[194:195], v[76:77], v[114:115]
	v_pk_mul_f32 v[164:165], v[72:73], v[118:119]
	v_pk_mul_f32 v[196:197], v[76:77], v[118:119]
	v_pk_mul_f32 v[166:167], v[72:73], v[122:123]
	v_pk_mul_f32 v[198:199], v[76:77], v[122:123]
	v_pk_fma_f32 v[160:161], v[70:71], v[112:113], v[160:161]
	v_pk_fma_f32 v[192:193], v[74:75], v[112:113], v[192:193]
	v_pk_fma_f32 v[162:163], v[70:71], v[116:117], v[162:163]
	v_pk_fma_f32 v[194:195], v[74:75], v[116:117], v[194:195]
	v_pk_fma_f32 v[164:165], v[70:71], v[120:121], v[164:165]
	v_pk_fma_f32 v[196:197], v[74:75], v[120:121], v[196:197]
	v_pk_fma_f32 v[166:167], v[70:71], v[124:125], v[166:167]
	v_pk_fma_f32 v[198:199], v[74:75], v[124:125], v[198:199]
	ds_read_b128 v[228:231], v100 offset:49152
	ds_read_b128 v[232:235], v100 offset:53248
	ds_read_b128 v[236:239], v100 offset:57344
	ds_read_b128 v[240:243], v100 offset:61440
	s_waitcnt lgkmcnt(8)
; #define LAS __attribute__((address_space(3)))
; __device__ __forceinline__ float dot4(const f32x4 a, const f32x4 b) { return (a[0] * b[0] + a[1] * b[1]) + (a[2] * b[2] + a[3] * b[3]); }
; __device__ __forceinline__ void norm_rows2(const f32x4 (&xa)[4], const f32x4 (&xb)[4], const LAS float* gsa, const LAS float* sha, const LAS float* gsb, const LAS float* shb, const LAS float* WgT, ...
;     ...
;     f32x4 pa[4], pb[4];
; #pragma unroll
;     for (int jq = 0; jq < 4; ++jq) { f32x4 sa = (f32x4){0.f, 0.f, 0.f, 0.f}, sb = sa;
; #pragma unroll
;         for (int i = 0; i < 4; ++i) { const LAS float* wp = WgT + (jq * 4) * 1024 + i * 256 + lane * 4;
;             const f32x4 w0 = *(const LAS f32x4*)wp, w1 = *(const LAS f32x4*)(wp + 1024), w2 = *(const LAS f32x4*)(wp + 2048), w3 = *(const LAS f32x4*)(wp + 3072);
;             sa += (f32x4){dot4(ya[i], w0), dot4(ya[i], w1), dot4(ya[i], w2), dot4(ya[i], w3)};
;             sb += (f32x4){dot4(yb[i], w0), dot4(yb[i], w1), dot4(yb[i], w2), dot4(yb[i], w3)}; }
;         pa[jq] = sa; pb[jq] = sb; }
	v_pk_mul_f32 v[168:169], v[72:73], v[126:127]
	v_pk_mul_f32 v[200:201], v[76:77], v[126:127]
	v_pk_mul_f32 v[170:171], v[72:73], v[130:131]
	v_pk_mul_f32 v[202:203], v[76:77], v[130:131]
	v_pk_mul_f32 v[172:173], v[72:73], v[134:135]
	v_pk_mul_f32 v[204:205], v[76:77], v[134:135]
	v_pk_mul_f32 v[174:175], v[72:73], v[138:139]
	v_pk_mul_f32 v[206:207], v[76:77], v[138:139]
	v_pk_fma_f32 v[168:169], v[70:71], v[128:129], v[168:169]
	v_pk_fma_f32 v[200:201], v[74:75], v[128:129], v[200:201]
	v_pk_fma_f32 v[170:171], v[70:71], v[132:133], v[170:171]
	v_pk_fma_f32 v[202:203], v[74:75], v[132:133], v[202:203]
	v_pk_fma_f32 v[172:173], v[70:71], v[136:137], v[172:173]
	v_pk_fma_f32 v[204:205], v[74:75], v[136:137], v[204:205]
	v_pk_fma_f32 v[174:175], v[70:71], v[140:141], v[174:175]
	v_pk_fma_f32 v[206:207], v[74:75], v[140:141], v[206:207]
	ds_read_b128 v[110:113], v99 offset:17408
	ds_read_b128 v[114:117], v99 offset:21504
	ds_read_b128 v[118:121], v99 offset:25600
	ds_read_b128 v[122:125], v99 offset:29696
	s_waitcnt lgkmcnt(8)
	v_pk_mul_f32 v[176:177], v[72:73], v[142:143]
	v_pk_mul_f32 v[208:209], v[76:77], v[142:143]
	v_pk_mul_f32 v[178:179], v[72:73], v[146:147]
	v_pk_mul_f32 v[210:211], v[76:77], v[146:147]
	v_pk_mul_f32 v[180:181], v[72:73], v[150:151]
	v_pk_mul_f32 v[212:213], v[76:77], v[150:151]
	v_pk_mul_f32 v[182:183], v[72:73], v[154:155]
	v_pk_mul_f32 v[214:215], v[76:77], v[154:155]
	v_pk_fma_f32 v[176:177], v[70:71], v[144:145], v[176:177]
	v_pk_fma_f32 v[208:209], v[74:75], v[144:145], v[208:209]
	v_pk_fma_f32 v[178:179], v[70:71], v[148:149], v[178:179]
	v_pk_fma_f32 v[210:211], v[74:75], v[148:149], v[210:211]
	v_pk_fma_f32 v[180:181], v[70:71], v[152:153], v[180:181]
	v_pk_fma_f32 v[212:213], v[74:75], v[152:153], v[212:213]
	v_pk_fma_f32 v[182:183], v[70:71], v[156:157], v[182:183]
	v_pk_fma_f32 v[214:215], v[74:75], v[156:157], v[214:215]
	ds_read_b128 v[126:129], v99 offset:33792
	ds_read_b128 v[130:133], v99 offset:37888
	ds_read_b128 v[134:137], v99 offset:41984
	ds_read_b128 v[138:141], v99 offset:46080
	s_waitcnt lgkmcnt(8)
	v_pk_mul_f32 v[184:185], v[72:73], v[228:229]
	v_pk_mul_f32 v[216:217], v[76:77], v[228:229]
	v_pk_mul_f32 v[186:187], v[72:73], v[232:233]
	v_pk_mul_f32 v[218:219], v[76:77], v[232:233]
	v_pk_mul_f32 v[188:189], v[72:73], v[236:237]
	v_pk_mul_f32 v[220:221], v[76:77], v[236:237]
	v_pk_mul_f32 v[190:191], v[72:73], v[240:241]
	v_pk_mul_f32 v[222:223], v[76:77], v[240:241]
	v_pk_fma_f32 v[184:185], v[70:71], v[230:231], v[184:185]
	v_pk_fma_f32 v[216:217], v[74:75], v[230:231], v[216:217]
	v_pk_fma_f32 v[186:187], v[70:71], v[234:235], v[186:187]
	v_pk_fma_f32 v[218:219], v[74:75], v[234:235], v[218:219]
	v_pk_fma_f32 v[188:189], v[70:71], v[238:239], v[188:189]
	v_pk_fma_f32 v[220:221], v[74:75], v[238:239], v[220:221]
	v_pk_fma_f32 v[190:191], v[70:71], v[242:243], v[190:191]
	v_pk_fma_f32 v[222:223], v[74:75], v[242:243], v[222:223]
	ds_read_b128 v[142:145], v99 offset:50176
	ds_read_b128 v[146:149], v99 offset:54272
	ds_read_b128 v[150:153], v99 offset:58368
	ds_read_b128 v[154:157], v99 offset:62464
	s_waitcnt lgkmcnt(8)
	v_pk_fma_f32 v[160:161], v[64:65], v[110:111], v[160:161]
	v_pk_fma_f32 v[192:193], v[68:69], v[110:111], v[192:193]
	v_pk_fma_f32 v[162:163], v[64:65], v[114:115], v[162:163]
	v_pk_fma_f32 v[194:195], v[68:69], v[114:115], v[194:195]
	v_pk_fma_f32 v[164:165], v[64:65], v[118:119], v[164:165]
	v_pk_fma_f32 v[196:197], v[68:69], v[118:119], v[196:197]
	v_pk_fma_f32 v[166:167], v[64:65], v[122:123], v[166:167]
	v_pk_fma_f32 v[198:199], v[68:69], v[122:123], v[198:199]
	v_pk_fma_f32 v[160:161], v[30:31], v[112:113], v[160:161]
	v_pk_fma_f32 v[192:193], v[66:67], v[112:113], v[192:193]
	v_pk_fma_f32 v[162:163], v[30:31], v[116:117], v[162:163]
	v_pk_fma_f32 v[194:195], v[66:67], v[116:117], v[194:195]
	v_pk_fma_f32 v[164:165], v[30:31], v[120:121], v[164:165]
	v_pk_fma_f32 v[196:197], v[66:67], v[120:121], v[196:197]
	v_pk_fma_f32 v[166:167], v[30:31], v[124:125], v[166:167]
	v_pk_fma_f32 v[198:199], v[66:67], v[124:125], v[198:199]
	ds_read_b128 v[228:231], v100 offset:50176
	ds_read_b128 v[232:235], v100 offset:54272
	ds_read_b128 v[236:239], v100 offset:58368
	ds_read_b128 v[240:243], v100 offset:62464
	s_waitcnt lgkmcnt(8)
	v_pk_fma_f32 v[168:169], v[64:65], v[126:127], v[168:169]
	v_pk_fma_f32 v[200:201], v[68:69], v[126:127], v[200:201]
	v_pk_fma_f32 v[170:171], v[64:65], v[130:131], v[170:171]
	v_pk_fma_f32 v[202:203], v[68:69], v[130:131], v[202:203]
	v_pk_fma_f32 v[172:173], v[64:65], v[134:135], v[172:173]
	v_pk_fma_f32 v[204:205], v[68:69], v[134:135], v[204:205]
	v_pk_fma_f32 v[174:175], v[64:65], v[138:139], v[174:175]
	v_pk_fma_f32 v[206:207], v[68:69], v[138:139], v[206:207]
	v_pk_fma_f32 v[168:169], v[30:31], v[128:129], v[168:169]
	v_pk_fma_f32 v[200:201], v[66:67], v[128:129], v[200:201]
	v_pk_fma_f32 v[170:171], v[30:31], v[132:133], v[170:171]
	v_pk_fma_f32 v[202:203], v[66:67], v[132:133], v[202:203]
	v_pk_fma_f32 v[172:173], v[30:31], v[136:137], v[172:173]
	v_pk_fma_f32 v[204:205], v[66:67], v[136:137], v[204:205]
	v_pk_fma_f32 v[174:175], v[30:31], v[140:141], v[174:175]
	v_pk_fma_f32 v[206:207], v[66:67], v[140:141], v[206:207]
	ds_read_b128 v[110:113], v99 offset:18432
	ds_read_b128 v[114:117], v99 offset:22528
	ds_read_b128 v[118:121], v99 offset:26624
	ds_read_b128 v[122:125], v99 offset:30720
	s_waitcnt lgkmcnt(8)
; #define LAS __attribute__((address_space(3)))
; __device__ __forceinline__ float dot4(const f32x4 a, const f32x4 b) { return (a[0] * b[0] + a[1] * b[1]) + (a[2] * b[2] + a[3] * b[3]); }
; __device__ __forceinline__ void norm_rows2(const f32x4 (&xa)[4], const f32x4 (&xb)[4], const LAS float* gsa, const LAS float* sha, const LAS float* gsb, const LAS float* shb, const LAS float* WgT, ...
;     ...
;     f32x4 pa[4], pb[4];
; #pragma unroll
;     for (int jq = 0; jq < 4; ++jq) { f32x4 sa = (f32x4){0.f, 0.f, 0.f, 0.f}, sb = sa;
; #pragma unroll
;         for (int i = 0; i < 4; ++i) { const LAS float* wp = WgT + (jq * 4) * 1024 + i * 256 + lane * 4;
;             const f32x4 w0 = *(const LAS f32x4*)wp, w1 = *(const LAS f32x4*)(wp + 1024), w2 = *(const LAS f32x4*)(wp + 2048), w3 = *(const LAS f32x4*)(wp + 3072);
;             sa += (f32x4){dot4(ya[i], w0), dot4(ya[i], w1), dot4(ya[i], w2), dot4(ya[i], w3)};
;             sb += (f32x4){dot4(yb[i], w0), dot4(yb[i], w1), dot4(yb[i], w2), dot4(yb[i], w3)}; }
;         pa[jq] = sa; pb[jq] = sb; }
	v_pk_fma_f32 v[176:177], v[64:65], v[142:143], v[176:177]
	v_pk_fma_f32 v[208:209], v[68:69], v[142:143], v[208:209]
	v_pk_fma_f32 v[178:179], v[64:65], v[146:147], v[178:179]
	v_pk_fma_f32 v[210:211], v[68:69], v[146:147], v[210:211]
	v_pk_fma_f32 v[180:181], v[64:65], v[150:151], v[180:181]
	v_pk_fma_f32 v[212:213], v[68:69], v[150:151], v[212:213]
	v_pk_fma_f32 v[182:183], v[64:65], v[154:155], v[182:183]
	v_pk_fma_f32 v[214:215], v[68:69], v[154:155], v[214:215]
	v_pk_fma_f32 v[176:177], v[30:31], v[144:145], v[176:177]
	v_pk_fma_f32 v[208:209], v[66:67], v[144:145], v[208:209]
	v_pk_fma_f32 v[178:179], v[30:31], v[148:149], v[178:179]
	v_pk_fma_f32 v[210:211], v[66:67], v[148:149], v[210:211]
	v_pk_fma_f32 v[180:181], v[30:31], v[152:153], v[180:181]
	v_pk_fma_f32 v[212:213], v[66:67], v[152:153], v[212:213]
	v_pk_fma_f32 v[182:183], v[30:31], v[156:157], v[182:183]
	v_pk_fma_f32 v[214:215], v[66:67], v[156:157], v[214:215]
	ds_read_b128 v[126:129], v99 offset:34816
	ds_read_b128 v[130:133], v99 offset:38912
	ds_read_b128 v[134:137], v99 offset:43008
	ds_read_b128 v[138:141], v99 offset:47104
	s_waitcnt lgkmcnt(8)
	v_pk_fma_f32 v[184:185], v[64:65], v[228:229], v[184:185]
	v_pk_fma_f32 v[216:217], v[68:69], v[228:229], v[216:217]
	v_pk_fma_f32 v[186:187], v[64:65], v[232:233], v[186:187]
	v_pk_fma_f32 v[218:219], v[68:69], v[232:233], v[218:219]
	v_pk_fma_f32 v[188:189], v[64:65], v[236:237], v[188:189]
	v_pk_fma_f32 v[220:221], v[68:69], v[236:237], v[220:221]
	v_pk_fma_f32 v[190:191], v[64:65], v[240:241], v[190:191]
	v_pk_fma_f32 v[222:223], v[68:69], v[240:241], v[222:223]
	v_pk_fma_f32 v[184:185], v[30:31], v[230:231], v[184:185]
	v_pk_fma_f32 v[216:217], v[66:67], v[230:231], v[216:217]
	v_pk_fma_f32 v[186:187], v[30:31], v[234:235], v[186:187]
	v_pk_fma_f32 v[218:219], v[66:67], v[234:235], v[218:219]
	v_pk_fma_f32 v[188:189], v[30:31], v[238:239], v[188:189]
	v_pk_fma_f32 v[220:221], v[66:67], v[238:239], v[220:221]
	v_pk_fma_f32 v[190:191], v[30:31], v[242:243], v[190:191]
	v_pk_fma_f32 v[222:223], v[66:67], v[242:243], v[222:223]
	ds_read_b128 v[142:145], v99 offset:51200
	ds_read_b128 v[146:149], v99 offset:55296
	ds_read_b128 v[150:153], v99 offset:59392
	ds_read_b128 v[154:157], v99 offset:63488
	s_waitcnt lgkmcnt(8)
	v_pk_fma_f32 v[160:161], v[20:21], v[110:111], v[160:161]
	v_pk_fma_f32 v[192:193], v[18:19], v[110:111], v[192:193]
	v_pk_fma_f32 v[162:163], v[20:21], v[114:115], v[162:163]
	v_pk_fma_f32 v[194:195], v[18:19], v[114:115], v[194:195]
	v_pk_fma_f32 v[164:165], v[20:21], v[118:119], v[164:165]
	v_pk_fma_f32 v[196:197], v[18:19], v[118:119], v[196:197]
	v_pk_fma_f32 v[166:167], v[20:21], v[122:123], v[166:167]
	v_pk_fma_f32 v[198:199], v[18:19], v[122:123], v[198:199]
	v_pk_fma_f32 v[160:161], v[16:17], v[112:113], v[160:161]
	v_pk_fma_f32 v[192:193], v[14:15], v[112:113], v[192:193]
	v_pk_fma_f32 v[162:163], v[16:17], v[116:117], v[162:163]
	v_pk_fma_f32 v[194:195], v[14:15], v[116:117], v[194:195]
	v_pk_fma_f32 v[164:165], v[16:17], v[120:121], v[164:165]
	v_pk_fma_f32 v[196:197], v[14:15], v[120:121], v[196:197]
	v_pk_fma_f32 v[166:167], v[16:17], v[124:125], v[166:167]
	v_pk_fma_f32 v[198:199], v[14:15], v[124:125], v[198:199]
	ds_read_b128 v[228:231], v100 offset:51200
	ds_read_b128 v[232:235], v100 offset:55296
	ds_read_b128 v[236:239], v100 offset:59392
	ds_read_b128 v[240:243], v100 offset:63488
	s_waitcnt lgkmcnt(8)
	v_pk_fma_f32 v[168:169], v[20:21], v[126:127], v[168:169]
	v_pk_fma_f32 v[200:201], v[18:19], v[126:127], v[200:201]
	v_pk_fma_f32 v[170:171], v[20:21], v[130:131], v[170:171]
	v_pk_fma_f32 v[202:203], v[18:19], v[130:131], v[202:203]
	v_pk_fma_f32 v[172:173], v[20:21], v[134:135], v[172:173]
	v_pk_fma_f32 v[204:205], v[18:19], v[134:135], v[204:205]
	v_pk_fma_f32 v[174:175], v[20:21], v[138:139], v[174:175]
	v_pk_fma_f32 v[206:207], v[18:19], v[138:139], v[206:207]
	v_pk_fma_f32 v[168:169], v[16:17], v[128:129], v[168:169]
	v_pk_fma_f32 v[200:201], v[14:15], v[128:129], v[200:201]
	v_pk_fma_f32 v[170:171], v[16:17], v[132:133], v[170:171]
	v_pk_fma_f32 v[202:203], v[14:15], v[132:133], v[202:203]
	v_pk_fma_f32 v[172:173], v[16:17], v[136:137], v[172:173]
	v_pk_fma_f32 v[204:205], v[14:15], v[136:137], v[204:205]
	v_pk_fma_f32 v[174:175], v[16:17], v[140:141], v[174:175]
	v_pk_fma_f32 v[206:207], v[14:15], v[140:141], v[206:207]
	ds_read_b128 v[110:113], v99 offset:19456
	ds_read_b128 v[114:117], v99 offset:23552
	ds_read_b128 v[118:121], v99 offset:27648
	ds_read_b128 v[122:125], v99 offset:31744
	s_waitcnt lgkmcnt(8)
	v_pk_fma_f32 v[176:177], v[20:21], v[142:143], v[176:177]
	v_pk_fma_f32 v[208:209], v[18:19], v[142:143], v[208:209]
	v_pk_fma_f32 v[178:179], v[20:21], v[146:147], v[178:179]
	v_pk_fma_f32 v[210:211], v[18:19], v[146:147], v[210:211]
	v_pk_fma_f32 v[180:181], v[20:21], v[150:151], v[180:181]
	v_pk_fma_f32 v[212:213], v[18:19], v[150:151], v[212:213]
	v_pk_fma_f32 v[182:183], v[20:21], v[154:155], v[182:183]
	v_pk_fma_f32 v[214:215], v[18:19], v[154:155], v[214:215]
	v_pk_fma_f32 v[176:177], v[16:17], v[144:145], v[176:177]
	v_pk_fma_f32 v[208:209], v[14:15], v[144:145], v[208:209]
	v_pk_fma_f32 v[178:179], v[16:17], v[148:149], v[178:179]
	v_pk_fma_f32 v[210:211], v[14:15], v[148:149], v[210:211]
	v_pk_fma_f32 v[180:181], v[16:17], v[152:153], v[180:181]
	v_pk_fma_f32 v[212:213], v[14:15], v[152:153], v[212:213]
	v_pk_fma_f32 v[182:183], v[16:17], v[156:157], v[182:183]
	v_pk_fma_f32 v[214:215], v[14:15], v[156:157], v[214:215]
	ds_read_b128 v[126:129], v99 offset:35840
	ds_read_b128 v[130:133], v99 offset:39936
	ds_read_b128 v[134:137], v99 offset:44032
	ds_read_b128 v[138:141], v99 offset:48128
	s_waitcnt lgkmcnt(8)
; #define LAS __attribute__((address_space(3)))
; __device__ __forceinline__ float dot4(const f32x4 a, const f32x4 b) { return (a[0] * b[0] + a[1] * b[1]) + (a[2] * b[2] + a[3] * b[3]); }
; __device__ __forceinline__ void norm_rows2(const f32x4 (&xa)[4], const f32x4 (&xb)[4], const LAS float* gsa, const LAS float* sha, const LAS float* gsb, const LAS float* shb, const LAS float* WgT, ...
;     ...
;     f32x4 pa[4], pb[4];
; #pragma unroll
;     for (int jq = 0; jq < 4; ++jq) { f32x4 sa = (f32x4){0.f, 0.f, 0.f, 0.f}, sb = sa;
; #pragma unroll
;         for (int i = 0; i < 4; ++i) { const LAS float* wp = WgT + (jq * 4) * 1024 + i * 256 + lane * 4;
;             const f32x4 w0 = *(const LAS f32x4*)wp, w1 = *(const LAS f32x4*)(wp + 1024), w2 = *(const LAS f32x4*)(wp + 2048), w3 = *(const LAS f32x4*)(wp + 3072);
;             sa += (f32x4){dot4(ya[i], w0), dot4(ya[i], w1), dot4(ya[i], w2), dot4(ya[i], w3)};
;             sb += (f32x4){dot4(yb[i], w0), dot4(yb[i], w1), dot4(yb[i], w2), dot4(yb[i], w3)}; }
;         pa[jq] = sa; pb[jq] = sb; }
	v_pk_fma_f32 v[184:185], v[20:21], v[228:229], v[184:185]
	v_pk_fma_f32 v[216:217], v[18:19], v[228:229], v[216:217]
	v_pk_fma_f32 v[186:187], v[20:21], v[232:233], v[186:187]
	v_pk_fma_f32 v[218:219], v[18:19], v[232:233], v[218:219]
	v_pk_fma_f32 v[188:189], v[20:21], v[236:237], v[188:189]
	v_pk_fma_f32 v[220:221], v[18:19], v[236:237], v[220:221]
	v_pk_fma_f32 v[190:191], v[20:21], v[240:241], v[190:191]
	v_pk_fma_f32 v[222:223], v[18:19], v[240:241], v[222:223]
	v_pk_fma_f32 v[184:185], v[16:17], v[230:231], v[184:185]
	v_pk_fma_f32 v[216:217], v[14:15], v[230:231], v[216:217]
	v_pk_fma_f32 v[186:187], v[16:17], v[234:235], v[186:187]
	v_pk_fma_f32 v[218:219], v[14:15], v[234:235], v[218:219]
	v_pk_fma_f32 v[188:189], v[16:17], v[238:239], v[188:189]
	v_pk_fma_f32 v[220:221], v[14:15], v[238:239], v[220:221]
	v_pk_fma_f32 v[190:191], v[16:17], v[242:243], v[190:191]
	v_pk_fma_f32 v[222:223], v[14:15], v[242:243], v[222:223]
	ds_read_b128 v[142:145], v99 offset:52224
	ds_read_b128 v[146:149], v99 offset:56320
	ds_read_b128 v[150:153], v99 offset:60416
	ds_read_b128 v[154:157], v99 offset:64512
	s_waitcnt lgkmcnt(8)
	v_pk_fma_f32 v[160:161], v[8:9], v[110:111], v[160:161]
	v_pk_fma_f32 v[192:193], v[12:13], v[110:111], v[192:193]
	v_pk_fma_f32 v[162:163], v[8:9], v[114:115], v[162:163]
	v_pk_fma_f32 v[194:195], v[12:13], v[114:115], v[194:195]
	v_pk_fma_f32 v[164:165], v[8:9], v[118:119], v[164:165]
	v_pk_fma_f32 v[196:197], v[12:13], v[118:119], v[196:197]
	v_pk_fma_f32 v[166:167], v[8:9], v[122:123], v[166:167]
	v_pk_fma_f32 v[198:199], v[12:13], v[122:123], v[198:199]
	v_pk_fma_f32 v[160:161], v[6:7], v[112:113], v[160:161]
	v_pk_fma_f32 v[192:193], v[10:11], v[112:113], v[192:193]
	v_pk_fma_f32 v[162:163], v[6:7], v[116:117], v[162:163]
	v_pk_fma_f32 v[194:195], v[10:11], v[116:117], v[194:195]
	v_pk_fma_f32 v[164:165], v[6:7], v[120:121], v[164:165]
	v_pk_fma_f32 v[196:197], v[10:11], v[120:121], v[196:197]
	v_pk_fma_f32 v[166:167], v[6:7], v[124:125], v[166:167]
	v_pk_fma_f32 v[198:199], v[10:11], v[124:125], v[198:199]
	ds_read_b128 v[228:231], v100 offset:52224
	ds_read_b128 v[232:235], v100 offset:56320
	ds_read_b128 v[236:239], v100 offset:60416
	ds_read_b128 v[240:243], v100 offset:64512
	s_waitcnt lgkmcnt(8)
	v_pk_fma_f32 v[168:169], v[8:9], v[126:127], v[168:169]
	v_pk_fma_f32 v[200:201], v[12:13], v[126:127], v[200:201]
	v_pk_fma_f32 v[170:171], v[8:9], v[130:131], v[170:171]
	v_pk_fma_f32 v[202:203], v[12:13], v[130:131], v[202:203]
	v_pk_fma_f32 v[172:173], v[8:9], v[134:135], v[172:173]
	v_pk_fma_f32 v[204:205], v[12:13], v[134:135], v[204:205]
	v_pk_fma_f32 v[174:175], v[8:9], v[138:139], v[174:175]
	v_pk_fma_f32 v[206:207], v[12:13], v[138:139], v[206:207]
	v_pk_fma_f32 v[168:169], v[6:7], v[128:129], v[168:169]
	v_pk_fma_f32 v[200:201], v[10:11], v[128:129], v[200:201]
	v_pk_fma_f32 v[170:171], v[6:7], v[132:133], v[170:171]
	v_pk_fma_f32 v[202:203], v[10:11], v[132:133], v[202:203]
	v_pk_fma_f32 v[172:173], v[6:7], v[136:137], v[172:173]
	v_pk_fma_f32 v[204:205], v[10:11], v[136:137], v[204:205]
	v_pk_fma_f32 v[174:175], v[6:7], v[140:141], v[174:175]
	v_pk_fma_f32 v[206:207], v[10:11], v[140:141], v[206:207]
	s_waitcnt lgkmcnt(4)
	v_pk_fma_f32 v[176:177], v[8:9], v[142:143], v[176:177]
	v_pk_fma_f32 v[208:209], v[12:13], v[142:143], v[208:209]
	v_pk_fma_f32 v[178:179], v[8:9], v[146:147], v[178:179]
	v_pk_fma_f32 v[210:211], v[12:13], v[146:147], v[210:211]
	v_pk_fma_f32 v[180:181], v[8:9], v[150:151], v[180:181]
	v_pk_fma_f32 v[212:213], v[12:13], v[150:151], v[212:213]
	v_pk_fma_f32 v[182:183], v[8:9], v[154:155], v[182:183]
	v_pk_fma_f32 v[214:215], v[12:13], v[154:155], v[214:215]
	v_pk_fma_f32 v[176:177], v[6:7], v[144:145], v[176:177]
	v_pk_fma_f32 v[208:209], v[10:11], v[144:145], v[208:209]
	v_pk_fma_f32 v[178:179], v[6:7], v[148:149], v[178:179]
	v_pk_fma_f32 v[210:211], v[10:11], v[148:149], v[210:211]
	v_pk_fma_f32 v[180:181], v[6:7], v[152:153], v[180:181]
	v_pk_fma_f32 v[212:213], v[10:11], v[152:153], v[212:213]
	v_pk_fma_f32 v[182:183], v[6:7], v[156:157], v[182:183]
	v_pk_fma_f32 v[214:215], v[10:11], v[156:157], v[214:215]
	s_waitcnt lgkmcnt(0)
	v_pk_fma_f32 v[184:185], v[8:9], v[228:229], v[184:185]
	v_pk_fma_f32 v[216:217], v[12:13], v[228:229], v[216:217]
	v_pk_fma_f32 v[186:187], v[8:9], v[232:233], v[186:187]
	v_pk_fma_f32 v[218:219], v[12:13], v[232:233], v[218:219]
	v_pk_fma_f32 v[188:189], v[8:9], v[236:237], v[188:189]
	v_pk_fma_f32 v[220:221], v[12:13], v[236:237], v[220:221]
	v_pk_fma_f32 v[190:191], v[8:9], v[240:241], v[190:191]
	v_pk_fma_f32 v[222:223], v[12:13], v[240:241], v[222:223]
	v_pk_fma_f32 v[184:185], v[6:7], v[230:231], v[184:185]
	v_pk_fma_f32 v[216:217], v[10:11], v[230:231], v[216:217]
	v_pk_fma_f32 v[186:187], v[6:7], v[234:235], v[186:187]
	v_pk_fma_f32 v[218:219], v[10:11], v[234:235], v[218:219]
	v_pk_fma_f32 v[188:189], v[6:7], v[238:239], v[188:189]
	v_pk_fma_f32 v[220:221], v[10:11], v[238:239], v[220:221]
	v_pk_fma_f32 v[190:191], v[6:7], v[242:243], v[190:191]
	v_pk_fma_f32 v[222:223], v[10:11], v[242:243], v[222:223]
	v_add_f32_e32 v22, v160, v161
	v_add_f32_e32 v23, v162, v163
	v_add_f32_e32 v24, v164, v165
	v_add_f32_e32 v25, v166, v167
	v_add_f32_e32 v78, v168, v169
	v_add_f32_e32 v79, v170, v171
	v_add_f32_e32 v80, v172, v173
	v_add_f32_e32 v81, v174, v175
	v_add_f32_e32 v86, v176, v177
	v_add_f32_e32 v87, v178, v179
	v_add_f32_e32 v88, v180, v181
	v_add_f32_e32 v89, v182, v183
	v_add_f32_e32 v2, v184, v185
	v_add_f32_e32 v3, v186, v187
	v_add_f32_e32 v0, v188, v189
	v_add_f32_e32 v1, v190, v191
	v_add_f32_e32 v26, v192, v193
	v_add_f32_e32 v27, v194, v195
; __device__ __forceinline__ float log_sigmoid(float x) { return fminf(x, 0.f) - log1pf(expf(-fabsf(x))); }
; __device__ __forceinline__ float bfly16(const f32x4 p0, const f32x4 p1, const f32x4 p2, const f32x4 p3, int lane) {
;     const bool b3 = lane & 8, b2 = lane & 4, b1 = lane & 2, b0 = lane & 1;
;     const f32x4 s0 = b3 ? p0 : p2, s1 = b3 ? p1 : p3, k0 = b3 ? p2 : p0, k1 = b3 ? p3 : p1;
;     f32x4 a, c;
;     a[0] = k0[0] + __shfl_xor(s0[0], 8); a[1] = k0[1] + __shfl_xor(s0[1], 8); a[2] = k0[2] + __shfl_xor(s0[2], 8); a[3] = k0[3] + __shfl_xor(s0[3], 8);
;     c[0] = k1[0] + __shfl_xor(s1[0], 8); c[1] = k1[1] + __shfl_xor(s1[1], 8); c[2] = k1[2] + __shfl_xor(s1[2], 8); c[3] = k1[3] + __shfl_xor(s1[3], 8);
;     const f32x4 s4 = b2 ? a : c, k4 = b2 ? c : a;
;     const float d0 = k4[0] + __shfl_xor(s4[0], 4), d1 = k4[1] + __shfl_xor(s4[1], 4), d2 = k4[2] + __shfl_xor(s4[2], 4), d3 = k4[3] + __shfl_xor(s4[3], 4);
;     const float e0 = (b1 ? d2 : d0) + __shfl_xor(b1 ? d0 : d2, 2), e1 = (b1 ? d3 : d1) + __shfl_xor(b1 ? d1 : d3, 2);
;     float q1 = (b0 ? e1 : e0) + __shfl_xor(b0 ? e0 : e1, 1);
;     q1 += __shfl_xor(q1, 16); q1 += __shfl_xor(q1, 32);
;     return q1;
; __device__ __forceinline__ void norm_rows2(const f32x4 (&xa)[4], const f32x4 (&xb)[4], const LAS float* gsa, const LAS float* sha, const LAS float* gsb, const LAS float* shb, const LAS float* WgT, ...
;     ...
;     const float qa = bfly16(pa[0], pa[1], pa[2], pa[3], lane), qb = bfly16(pb[0], pb[1], pb[2], pb[3], lane);
;     if (lane < 16) { const float gbv = gate_b[lane]; const bool ls = (lane >> 2) & 1;
;         const float prea = qa + gbv, preb = qb + gbv;
;         ga[0] = ls ? log_sigmoid(prea) : prea; gb[0] = ls ? log_sigmoid(preb) : preb; }
	v_add_f32_e32 v28, v196, v197
	v_add_f32_e32 v29, v198, v199
	v_add_f32_e32 v82, v200, v201
	v_add_f32_e32 v83, v202, v203
	v_add_f32_e32 v84, v204, v205
	v_add_f32_e32 v85, v206, v207
	v_add_f32_e32 v90, v208, v209
	v_add_f32_e32 v91, v210, v211
	v_add_f32_e32 v92, v212, v213
	v_add_f32_e32 v93, v214, v215
	v_add_f32_e32 v12, v216, v217
	v_add_f32_e32 v13, v218, v219
	v_add_f32_e32 v10, v220, v221
	v_add_f32_e32 v11, v222, v223
	v_cndmask_b32_e64 v21, v85, v11, s[6:7]
	v_cndmask_b32_e64 v20, v84, v10, s[6:7]
	v_add_f32_dpp v110, v22, v22 row_mirror row_mask:0xf bank_mask:0x3
	v_add_f32_dpp v110, v86, v86 row_mirror row_mask:0xf bank_mask:0xc
	v_add_f32_dpp v114, v78, v78 row_mirror row_mask:0xf bank_mask:0x3
	v_add_f32_dpp v114, v2, v2 row_mirror row_mask:0xf bank_mask:0xc
	v_add_f32_dpp v118, v26, v26 row_mirror row_mask:0xf bank_mask:0x3
	v_add_f32_dpp v118, v90, v90 row_mirror row_mask:0xf bank_mask:0xc
	v_add_f32_dpp v122, v82, v82 row_mirror row_mask:0xf bank_mask:0x3
	v_add_f32_dpp v122, v12, v12 row_mirror row_mask:0xf bank_mask:0xc
	v_add_f32_dpp v111, v23, v23 row_mirror row_mask:0xf bank_mask:0x3
	v_add_f32_dpp v111, v87, v87 row_mirror row_mask:0xf bank_mask:0xc
	v_add_f32_dpp v115, v79, v79 row_mirror row_mask:0xf bank_mask:0x3
	v_add_f32_dpp v115, v3, v3 row_mirror row_mask:0xf bank_mask:0xc
	v_add_f32_dpp v119, v27, v27 row_mirror row_mask:0xf bank_mask:0x3
	v_add_f32_dpp v119, v91, v91 row_mirror row_mask:0xf bank_mask:0xc
	v_add_f32_dpp v123, v83, v83 row_mirror row_mask:0xf bank_mask:0x3
	v_add_f32_dpp v123, v13, v13 row_mirror row_mask:0xf bank_mask:0xc
	v_add_f32_dpp v112, v24, v24 row_mirror row_mask:0xf bank_mask:0x3
	v_add_f32_dpp v112, v88, v88 row_mirror row_mask:0xf bank_mask:0xc
	v_add_f32_dpp v116, v80, v80 row_mirror row_mask:0xf bank_mask:0x3
	v_add_f32_dpp v116, v0, v0 row_mirror row_mask:0xf bank_mask:0xc
	v_add_f32_dpp v120, v28, v28 row_mirror row_mask:0xf bank_mask:0x3
	v_add_f32_dpp v120, v92, v92 row_mirror row_mask:0xf bank_mask:0xc
	v_add_f32_dpp v124, v84, v84 row_mirror row_mask:0xf bank_mask:0x3
	v_add_f32_dpp v124, v10, v10 row_mirror row_mask:0xf bank_mask:0xc
	v_add_f32_dpp v113, v25, v25 row_mirror row_mask:0xf bank_mask:0x3
	v_add_f32_dpp v113, v89, v89 row_mirror row_mask:0xf bank_mask:0xc
	v_add_f32_dpp v117, v81, v81 row_mirror row_mask:0xf bank_mask:0x3
	v_add_f32_dpp v117, v1, v1 row_mirror row_mask:0xf bank_mask:0xc
	v_add_f32_dpp v121, v29, v29 row_mirror row_mask:0xf bank_mask:0x3
	v_add_f32_dpp v121, v93, v93 row_mirror row_mask:0xf bank_mask:0xc
	v_add_f32_dpp v125, v85, v85 row_mirror row_mask:0xf bank_mask:0x3
	v_add_f32_dpp v125, v11, v11 row_mirror row_mask:0xf bank_mask:0xc
	v_add_f32_dpp v126, v110, v110 row_half_mirror row_mask:0xf bank_mask:0x5
	v_add_f32_dpp v126, v114, v114 row_half_mirror row_mask:0xf bank_mask:0xa
	v_add_f32_dpp v130, v118, v118 row_half_mirror row_mask:0xf bank_mask:0x5
	v_add_f32_dpp v130, v122, v122 row_half_mirror row_mask:0xf bank_mask:0xa
	v_add_f32_dpp v127, v111, v111 row_half_mirror row_mask:0xf bank_mask:0x5
	v_add_f32_dpp v127, v115, v115 row_half_mirror row_mask:0xf bank_mask:0xa
	v_add_f32_dpp v131, v119, v119 row_half_mirror row_mask:0xf bank_mask:0x5
	v_add_f32_dpp v131, v123, v123 row_half_mirror row_mask:0xf bank_mask:0xa
	v_add_f32_dpp v128, v112, v112 row_half_mirror row_mask:0xf bank_mask:0x5
	v_add_f32_dpp v128, v116, v116 row_half_mirror row_mask:0xf bank_mask:0xa
	v_add_f32_dpp v132, v120, v120 row_half_mirror row_mask:0xf bank_mask:0x5
	v_add_f32_dpp v132, v124, v124 row_half_mirror row_mask:0xf bank_mask:0xa
	v_add_f32_dpp v129, v113, v113 row_half_mirror row_mask:0xf bank_mask:0x5
	v_add_f32_dpp v129, v117, v117 row_half_mirror row_mask:0xf bank_mask:0xa
	v_add_f32_dpp v133, v121, v121 row_half_mirror row_mask:0xf bank_mask:0x5
	v_add_f32_dpp v133, v125, v125 row_half_mirror row_mask:0xf bank_mask:0xa
	v_cndmask_b32_e64 v134, v128, v126, s[12:13]
	v_cndmask_b32_e64 v135, v126, v128, s[12:13]
	v_cndmask_b32_e64 v136, v129, v127, s[12:13]
	v_cndmask_b32_e64 v137, v127, v129, s[12:13]
	v_cndmask_b32_e64 v138, v132, v130, s[12:13]
	v_cndmask_b32_e64 v139, v130, v132, s[12:13]
	v_cndmask_b32_e64 v140, v133, v131, s[12:13]
	v_cndmask_b32_e64 v141, v131, v133, s[12:13]
	v_add_f32_dpp v134, v135, v134 quad_perm:[2,3,0,1] row_mask:0xf bank_mask:0xf
	v_add_f32_dpp v136, v137, v136 quad_perm:[2,3,0,1] row_mask:0xf bank_mask:0xf
	v_add_f32_dpp v138, v139, v138 quad_perm:[2,3,0,1] row_mask:0xf bank_mask:0xf
	v_add_f32_dpp v140, v141, v140 quad_perm:[2,3,0,1] row_mask:0xf bank_mask:0xf
	v_cndmask_b32_e64 v143, v134, v136, s[14:15]
	v_cndmask_b32_e64 v127, v138, v140, s[14:15]
	v_cndmask_b32_e64 v142, v136, v134, s[14:15]
	v_cndmask_b32_e64 v126, v140, v138, s[14:15]
	v_add_f32_dpp v1, v143, v142 quad_perm:[1,0,3,2] row_mask:0xf bank_mask:0xf
	v_add_f32_dpp v0, v127, v126 quad_perm:[1,0,3,2] row_mask:0xf bank_mask:0xf
	v_mov_b32_e32 v2, v0
	v_mov_b32_e32 v3, v1
	s_nop 1
	v_permlane16_swap_b32_e32 v2, v0
	v_permlane16_swap_b32_e32 v3, v1
	s_waitcnt lgkmcnt(0)
	v_pk_add_f32 v[0:1], v[0:1], v[2:3]
	v_mov_b32_e32 v2, v0
	v_mov_b32_e32 v3, v1
	s_nop 1
	v_permlane32_swap_b32_e32 v2, v0
	v_permlane32_swap_b32_e32 v3, v1
	s_and_saveexec_b64 s[30:31], s[16:17]
	s_cbranch_execz .LBB0_109
	global_load_dword v4, v[44:45], off
	s_waitcnt lgkmcnt(0)
	v_pk_add_f32 v[0:1], v[0:1], v[2:3]
	s_waitcnt vmcnt(0)
	v_pk_add_f32 v[0:1], v[0:1], v[4:5] op_sel_hi:[1,0]
	s_and_saveexec_b64 s[80:81], s[10:11]
	s_cbranch_execz .LBB0_108
; __device__ __forceinline__ float log_sigmoid(float x) { return fminf(x, 0.f) - log1pf(expf(-fabsf(x))); }
; __device__ __forceinline__ void norm_rows2(const f32x4 (&xa)[4], const f32x4 (&xb)[4], const LAS float* gsa, const LAS float* sha, const LAS float* gsb, const LAS float* shb, const LAS float* WgT, ...
;     ...
;     if (lane < 16) { const float gbv = gate_b[lane]; const bool ls = (lane >> 2) & 1;
;         const float prea = qa + gbv, preb = qb + gbv;
;         ga[0] = ls ? log_sigmoid(prea) : prea; gb[0] = ls ? log_sigmoid(preb) : preb; }
	v_mul_f32_e64 v2, |v0|, s35
	v_rndne_f32_e32 v3, v2
	v_sub_f32_e32 v4, v2, v3
	v_fma_f32 v2, |v0|, s35, -v2
	v_fma_f32 v2, |v0|, s47, v2
	v_add_f32_e32 v2, v4, v2
	v_exp_f32_e32 v4, v2
	v_cvt_i32_f32_e32 v3, v3
	v_cmp_ngt_f32_e64 s[28:29], |v0|, s53
	v_max_f32_e32 v2, v0, v0
	v_min_f32_e32 v2, 0, v2
	v_ldexp_f32 v3, v4, v3
	v_cndmask_b32_e64 v3, 0, v3, s[28:29]
	v_cmp_nlt_f32_e64 s[28:29], |v0|, s75
	s_nop 1
	v_cndmask_b32_e64 v30, v107, v3, s[28:29]
	v_add_f32_e32 v6, 1.0, v30
	v_add_f32_e32 v0, -1.0, v6
	v_sub_f32_e32 v3, v0, v6
	v_add_f32_e32 v3, 1.0, v3
	v_sub_f32_e32 v0, v30, v0
	v_add_f32_e32 v7, v0, v3
	v_mul_f32_e64 v0, |v1|, s35
	v_rndne_f32_e32 v3, v0
	v_sub_f32_e32 v9, v0, v3
	v_fma_f32 v0, |v1|, s35, -v0
	v_fma_f32 v0, |v1|, s47, v0
	v_add_f32_e32 v0, v9, v0
	v_exp_f32_e32 v0, v0
	v_cvt_i32_f32_e32 v9, v3
	v_cmp_ngt_f32_e64 s[28:29], |v1|, s53
	v_cvt_f64_f32_e32 v[4:5], v6
	v_frexp_exp_i32_f64_e32 v4, v[4:5]
	v_ldexp_f32 v0, v0, v9
	v_cndmask_b32_e64 v0, 0, v0, s[28:29]
	v_cmp_nlt_f32_e64 s[28:29], |v1|, s75
	v_max_f32_e32 v3, v1, v1
	v_frexp_mant_f32_e32 v8, v6
	v_cndmask_b32_e64 v31, v107, v0, s[28:29]
	v_add_f32_e32 v5, 1.0, v31
	v_add_f32_e32 v0, -1.0, v5
	v_sub_f32_e32 v1, v0, v5
	v_add_f32_e32 v1, 1.0, v1
	v_sub_f32_e32 v0, v31, v0
	v_add_f32_e32 v9, v0, v1
	v_frexp_mant_f32_e32 v10, v5
	v_cvt_f64_f32_e32 v[0:1], v5
	v_frexp_exp_i32_f64_e32 v0, v[0:1]
	v_cmp_gt_f32_e64 s[28:29], s79, v10
	v_min_f32_e32 v3, 0, v3
	s_nop 0
	v_subbrev_co_u32_e64 v22, s[28:29], 0, v0, s[28:29]
	v_cmp_gt_f32_e64 s[28:29], s79, v8
	s_nop 1
	v_subbrev_co_u32_e64 v23, s[28:29], 0, v4, s[28:29]
	v_sub_u32_e32 v1, 0, v23
	v_ldexp_f32 v0, v6, v1
	v_sub_u32_e32 v6, 0, v22
	v_ldexp_f32 v4, v7, v1
	v_ldexp_f32 v1, v5, v6
	v_ldexp_f32 v5, v9, v6
	v_pk_add_f32 v[6:7], v[0:1], 1.0 op_sel_hi:[1,0]
	v_pk_add_f32 v[14:15], v[0:1], -1.0 op_sel_hi:[1,0]
	v_pk_add_f32 v[8:9], v[6:7], -1.0 op_sel_hi:[1,0]
	v_pk_add_f32 v[16:17], v[14:15], 1.0 op_sel_hi:[1,0]
	v_pk_add_f32 v[8:9], v[0:1], v[8:9] neg_lo:[0,1] neg_hi:[0,1]
	v_pk_add_f32 v[0:1], v[0:1], v[16:17] neg_lo:[0,1] neg_hi:[0,1]
	v_pk_add_f32 v[8:9], v[4:5], v[8:9]
	v_pk_add_f32 v[0:1], v[4:5], v[0:1]
	v_pk_add_f32 v[10:11], v[6:7], v[8:9]
	v_pk_add_f32 v[4:5], v[14:15], v[0:1]
	v_rcp_f32_e32 v12, v10
	v_rcp_f32_e32 v13, v11
	v_pk_add_f32 v[6:7], v[6:7], v[10:11] neg_lo:[0,1] neg_hi:[0,1]
	v_pk_add_f32 v[14:15], v[14:15], v[4:5] neg_lo:[0,1] neg_hi:[0,1]
	v_pk_add_f32 v[6:7], v[8:9], v[6:7]
	v_pk_mul_f32 v[8:9], v[4:5], v[12:13]
	v_pk_add_f32 v[0:1], v[0:1], v[14:15]
	v_pk_mul_f32 v[14:15], v[10:11], v[8:9]
	v_cmp_neq_f32_e64 s[28:29], s77, v30
	v_pk_fma_f32 v[16:17], v[8:9], v[10:11], v[14:15] neg_lo:[0,0,1] neg_hi:[0,0,1]
	s_nop 0
	v_pk_fma_f32 v[16:17], v[8:9], v[6:7], v[16:17]
	s_nop 0
	v_pk_add_f32 v[18:19], v[14:15], v[16:17]
	s_nop 0
	v_pk_add_f32 v[20:21], v[4:5], v[18:19] neg_lo:[0,1] neg_hi:[0,1]
	v_pk_add_f32 v[14:15], v[18:19], v[14:15] neg_lo:[0,1] neg_hi:[0,1]
	v_pk_add_f32 v[4:5], v[4:5], v[20:21] neg_lo:[0,1] neg_hi:[0,1]
	s_nop 0
	v_pk_add_f32 v[4:5], v[4:5], v[18:19] neg_lo:[0,1] neg_hi:[0,1]
	s_nop 0
	v_pk_add_f32 v[0:1], v[0:1], v[4:5]
	v_pk_add_f32 v[4:5], v[14:15], v[16:17] neg_lo:[0,1] neg_hi:[0,1]
	s_nop 0
	v_pk_add_f32 v[0:1], v[4:5], v[0:1]
	s_nop 0
	v_pk_add_f32 v[4:5], v[20:21], v[0:1]
	s_nop 0
	v_pk_mul_f32 v[14:15], v[12:13], v[4:5]
	s_nop 0
	v_pk_mul_f32 v[16:17], v[10:11], v[14:15]
	s_nop 0
	v_pk_fma_f32 v[10:11], v[14:15], v[10:11], v[16:17] neg_lo:[0,0,1] neg_hi:[0,0,1]
	s_nop 0
	v_pk_fma_f32 v[6:7], v[14:15], v[6:7], v[10:11]
	v_pk_add_f32 v[10:11], v[20:21], v[4:5] neg_lo:[0,1] neg_hi:[0,1]
	s_nop 0
	v_pk_add_f32 v[0:1], v[0:1], v[10:11]
	v_pk_add_f32 v[10:11], v[16:17], v[6:7]
	s_nop 0
	v_pk_add_f32 v[18:19], v[4:5], v[10:11] neg_lo:[0,1] neg_hi:[0,1]
	v_pk_add_f32 v[16:17], v[10:11], v[16:17] neg_lo:[0,1] neg_hi:[0,1]
	v_pk_add_f32 v[4:5], v[4:5], v[18:19] neg_lo:[0,1] neg_hi:[0,1]
	s_nop 0
	v_pk_add_f32 v[4:5], v[4:5], v[10:11] neg_lo:[0,1] neg_hi:[0,1]
	s_nop 0
	v_pk_add_f32 v[0:1], v[0:1], v[4:5]
	v_pk_add_f32 v[4:5], v[16:17], v[6:7] neg_lo:[0,1] neg_hi:[0,1]
	s_nop 0
	v_pk_add_f32 v[0:1], v[4:5], v[0:1]
; __device__ __forceinline__ float log_sigmoid(float x) { return fminf(x, 0.f) - log1pf(expf(-fabsf(x))); }
; __device__ __forceinline__ void norm_rows2(const f32x4 (&xa)[4], const f32x4 (&xb)[4], const LAS float* gsa, const LAS float* sha, const LAS float* gsb, const LAS float* shb, const LAS float* WgT, ...
;     ...
;     if (lane < 16) { const float gbv = gate_b[lane]; const bool ls = (lane >> 2) & 1;
;         const float prea = qa + gbv, preb = qb + gbv;
;         ga[0] = ls ? log_sigmoid(prea) : prea; gb[0] = ls ? log_sigmoid(preb) : preb; }
	v_pk_add_f32 v[4:5], v[8:9], v[14:15]
	v_pk_add_f32 v[0:1], v[18:19], v[0:1]
	v_pk_add_f32 v[6:7], v[4:5], v[8:9] neg_lo:[0,1] neg_hi:[0,1]
	v_pk_mul_f32 v[0:1], v[12:13], v[0:1]
	v_pk_add_f32 v[6:7], v[14:15], v[6:7] neg_lo:[0,1] neg_hi:[0,1]
	v_cvt_f32_i32_e32 v9, v22
	v_pk_add_f32 v[0:1], v[6:7], v[0:1]
	v_cvt_f32_i32_e32 v8, v23
	v_pk_add_f32 v[6:7], v[4:5], v[0:1]
	v_pk_mul_f32 v[14:15], v[8:9], s[76:77] op_sel_hi:[1,0]
	v_pk_mul_f32 v[10:11], v[6:7], v[6:7]
	v_pk_add_f32 v[4:5], v[6:7], v[4:5] neg_lo:[0,1] neg_hi:[0,1]
	v_pk_fma_f32 v[12:13], v[10:11], s[52:53], v[52:53] op_sel_hi:[1,0,0]
	v_pk_add_f32 v[0:1], v[0:1], v[4:5] neg_lo:[0,1] neg_hi:[0,1]
	v_ldexp_f32 v4, v6, 1
	v_pk_fma_f32 v[12:13], v[10:11], v[12:13], s[74:75] op_sel_hi:[1,1,0]
	v_ldexp_f32 v5, v7, 1
	v_pk_mul_f32 v[6:7], v[6:7], v[10:11]
	v_pk_fma_f32 v[16:17], v[8:9], s[76:77], v[14:15] op_sel_hi:[1,0,1] neg_lo:[0,0,1] neg_hi:[0,0,1]
	v_pk_mul_f32 v[6:7], v[6:7], v[12:13]
	v_mov_b32_e32 v19, v5
	v_pk_add_f32 v[10:11], v[4:5], v[6:7]
	v_ldexp_f32 v0, v0, 1
	v_pk_add_f32 v[4:5], v[10:11], v[4:5] neg_lo:[0,1] neg_hi:[0,1]
	v_pk_fma_f32 v[8:9], v[8:9], s[78:79], v[16:17] op_sel_hi:[1,0,1]
	v_ldexp_f32 v1, v1, 1
	v_pk_add_f32 v[4:5], v[6:7], v[4:5] neg_lo:[0,1] neg_hi:[0,1]
	v_mov_b32_e32 v12, v14
	v_mov_b32_e32 v13, v7
	v_mov_b32_e32 v18, v8
	v_pk_add_f32 v[6:7], v[0:1], v[4:5]
	v_mov_b32_e32 v4, v14
	v_mov_b32_e32 v0, v8
	v_pk_add_f32 v[12:13], v[12:13], v[18:19]
	v_pk_add_f32 v[18:19], v[4:5], v[0:1]
	v_mov_b32_e32 v0, v10
	v_mov_b32_e32 v4, v6
	v_pk_add_f32 v[16:17], v[14:15], v[8:9]
	v_pk_add_f32 v[0:1], v[0:1], v[4:5]
	v_pk_add_f32 v[4:5], v[10:11], v[6:7]
	v_mov_b32_e32 v20, v16
	v_mov_b32_e32 v21, v15
	v_mov_b32_e32 v22, v4
	v_mov_b32_e32 v23, v9
	v_pk_add_f32 v[0:1], v[12:13], v[0:1]
	v_pk_add_f32 v[12:13], v[16:17], v[4:5]
	v_pk_add_f32 v[24:25], v[20:21], v[22:23]
	v_mov_b32_e32 v26, v4
	v_mov_b32_e32 v27, v13
	v_mov_b32_e32 v28, v10
	v_mov_b32_e32 v29, v17
	v_pk_add_f32 v[20:21], v[24:25], v[20:21] neg_lo:[0,1] neg_hi:[0,1]
	v_pk_add_f32 v[26:27], v[26:27], v[28:29] neg_lo:[0,1] neg_hi:[0,1]
	v_pk_add_f32 v[24:25], v[16:17], v[14:15] neg_lo:[0,1] neg_hi:[0,1]
	v_pk_add_f32 v[22:23], v[22:23], v[20:21] neg_lo:[0,1] neg_hi:[0,1]
	v_mov_b32_e32 v28, v16
	v_mov_b32_e32 v29, v13
	v_mov_b32_e32 v15, v27
	v_mov_b32_e32 v21, v11
	v_pk_add_f32 v[10:11], v[4:5], v[10:11] neg_lo:[0,1] neg_hi:[0,1]
	v_pk_add_f32 v[14:15], v[28:29], v[14:15] neg_lo:[0,1] neg_hi:[0,1]
	v_pk_add_f32 v[24:25], v[8:9], v[24:25] neg_lo:[0,1] neg_hi:[0,1]
	v_pk_add_f32 v[0:1], v[0:1], v[20:21] neg_lo:[0,1] neg_hi:[0,1]
	v_pk_add_f32 v[10:11], v[6:7], v[10:11] neg_lo:[0,1] neg_hi:[0,1]
	v_mov_b32_e32 v9, v17
	v_mov_b32_e32 v7, v5
	v_pk_add_f32 v[0:1], v[18:19], v[0:1] neg_lo:[0,1] neg_hi:[0,1]
	v_pk_add_f32 v[8:9], v[8:9], v[14:15] neg_lo:[0,1] neg_hi:[0,1]
	v_pk_add_f32 v[4:5], v[6:7], v[26:27] neg_lo:[0,1] neg_hi:[0,1]
	v_pk_add_f32 v[14:15], v[22:23], v[0:1]
	v_pk_add_f32 v[6:7], v[4:5], v[8:9]
	v_mov_b32_e32 v5, v1
	v_pk_add_f32 v[0:1], v[24:25], v[4:5]
	v_mov_b32_e32 v9, v23
	v_pk_add_f32 v[0:1], v[0:1], v[8:9] neg_lo:[0,1] neg_hi:[0,1]
	v_mov_b32_e32 v4, v6
	v_mov_b32_e32 v5, v15
	v_pk_add_f32 v[4:5], v[4:5], v[0:1] neg_lo:[0,1] neg_hi:[0,1]
	v_pk_add_f32 v[0:1], v[10:11], v[0:1] neg_lo:[0,1] neg_hi:[0,1]
	v_pk_add_f32 v[4:5], v[8:9], v[4:5] neg_lo:[0,1] neg_hi:[0,1]
	s_nop 0
	v_pk_add_f32 v[0:1], v[0:1], v[4:5]
	v_pk_add_f32 v[4:5], v[14:15], v[6:7]
	s_nop 0
	v_pk_add_f32 v[6:7], v[12:13], v[4:5]
	s_nop 0
	v_pk_add_f32 v[8:9], v[6:7], v[12:13] neg_lo:[0,1] neg_hi:[0,1]
	s_nop 0
	v_pk_add_f32 v[4:5], v[4:5], v[8:9] neg_lo:[0,1] neg_hi:[0,1]
	s_nop 0
	v_pk_add_f32 v[0:1], v[0:1], v[4:5]
	s_nop 0
	v_pk_add_f32 v[0:1], v[6:7], v[0:1]
	s_nop 0
	v_cndmask_b32_e64 v0, v107, v0, s[28:29]
	v_cmp_neq_f32_e64 s[28:29], s77, v31
	s_nop 1
	v_cndmask_b32_e64 v1, v107, v1, s[28:29]
	v_cmp_lt_f32_e64 s[28:29], |v31|, s92
	s_nop 1
	v_cndmask_b32_e64 v1, v1, v31, s[28:29]
	v_cmp_lt_f32_e64 s[28:29], |v30|, s92
	s_nop 1
	v_cndmask_b32_e64 v0, v0, v30, s[28:29]
	v_pk_add_f32 v[0:1], v[2:3], v[0:1] neg_lo:[0,1] neg_hi:[0,1]
	s_branch .LBB0_108
